# add G3 gate-load hoist (issue 8 gate loads together)
# baseline (speedup 1.0000x reference)
; __device__ __forceinline__ unsigned pk2(float lo, float hi) { return pg8::pkc(lo, hi); }
; #define GLA_BAR() do { asm volatile("s_waitcnt lgkmcnt(0)" ::: "memory"); __builtin_amdgcn_s_barrier(); asm volatile("" ::: "memory"); } while (0)
; __device__ __forceinline__ void ph_g3(Frame& F, int e, int nrc) {
;     ...
;         GLA_BAR();
;         const int t = 32 * tb + r32;
;         const float tot = (SS[t] + SS[64 + t]) + (SS[128 + t] + SS[192 + t]);
;         const float rn = __builtin_amdgcn_rsqf(tot * (1.0f / 128.0f) + EPS);
;         const size_t row = (size_t)rc * 64 + t;
; #pragma unroll
;         for (int g4 = 0; g4 < 4; ++g4) { const int dv0 = 32 * db + 8 * g4 + 4 * hi;
;             const v2u gw = *(const v2u*)(P + row * DINP + C_GB + 128 * h + dv0); const f32x4 gn = *(const f32x4*)(gg + 128 * h + dv0);
;             const float g0 = bflo(gw.x), g1 = bfhi(gw.x), g2 = bflo(gw.y), g3 = bfhi(gw.y);
;             const float y0 = o[4 * g4 + 0] * rn * gn.x * (g0 * __builtin_amdgcn_rcpf(1.0f + __expf(-g0))), y1 = o[4 * g4 + 1] * rn * gn.y * (g1 * __builtin_amdgcn_rcpf(1.0f + __expf(-g1)));
;             const float y2 = o[4 * g4 + 2] * rn * gn.z * (g2 * __builtin_amdgcn_rcpf(1.0f + __expf(-g2))), y3 = o[4 * g4 + 3] * rn * gn.w * (g3 * __builtin_amdgcn_rcpf(1.0f + __expf(-g3)));
;             v2u w; w.x = pk2(y0, y1); w.y = pk2(y2, y3);
;             *(v2u*)(MIX + row * D + 1024 + 128 * h + dv0) = w; }
.LBB0_996:
	s_or_b64 exec, exec, s[18:19]
	s_waitcnt lgkmcnt(0)
	s_barrier
	ds_read2st64_b32 v[20:21], v151 offset0:216 offset1:217
	ds_read2st64_b32 v[22:23], v151 offset0:218 offset1:219
	s_ashr_i32 s18, s9, 3
	s_ashr_i32 s19, s18, 31
	s_lshl_b64 s[18:19], s[18:19], 6
	s_waitcnt lgkmcnt(1)
	v_mov_b32_e32 v24, v20
	s_waitcnt lgkmcnt(0)
	v_mov_b32_e32 v25, v22
	v_mov_b32_e32 v22, v21
	v_pk_add_f32 v[20:21], v[24:25], v[22:23]
	v_or_b32_e32 v22, s18, v142
	v_mov_b64_e32 v[24:25], s[12:13]
	s_movk_i32 s9, 0x3200
	v_add_f32_e32 v20, v20, v21
	v_mov_b32_e32 v23, s19
	v_mad_u64_u32 v[24:25], vcc, v22, s9, v[24:25]
	v_mov_b32_e32 v21, 0x3200
	s_and_b32 s9, s21, 0x380
	v_mad_i32_i24 v25, s19, v21, v25
	s_lshl_b32 s30, s9, 1
	v_lshlrev_b64 v[22:23], 12, v[22:23]
	v_lshl_add_u64 v[24:25], v[24:25], 0, s[30:31]
	v_lshl_add_u64 v[22:23], s[22:23], 0, v[22:23]
	v_lshl_add_u64 v[30:31], v[22:23], 0, s[30:31]
	v_lshl_add_u64 v[22:23], v[24:25], 0, v[146:147]
	s_mov_b64 s[18:19], 0x2800
	v_lshl_add_u64 v[24:25], v[22:23], 0, s[18:19]
	v_add_co_u32_e32 v22, vcc, s3, v22
	s_lshl_b32 s30, s9, 2
	s_nop 0
	v_addc_co_u32_e32 v23, vcc, 0, v23, vcc
	global_load_dwordx2 v[32:33], v[22:23], off offset:2048
	v_lshl_add_u64 v[22:23], v[144:145], 0, s[30:31]
	global_load_dwordx4 v[26:29], v[22:23], off
	global_load_dwordx2 v[162:163], v[24:25], off offset:16
	global_load_dwordx4 v[164:167], v[22:23], off offset:32
	global_load_dwordx2 v[168:169], v[24:25], off offset:32
	global_load_dwordx4 v[170:173], v[22:23], off offset:64
	global_load_dwordx2 v[174:175], v[24:25], off offset:48
	global_load_dwordx4 v[176:179], v[22:23], off offset:96
	v_fmamk_f32 v20, v20, 0x3c000000, v244
	v_rsq_f32_e32 v20, v20
	s_mov_b64 s[18:19], 0x21e00800
	s_mov_b32 s9, 0x21e00000
	s_waitcnt vmcnt(13)
	v_mov_b64_e32 v[44:45], v[84:85]
	v_mov_b64_e32 v[40:41], v[88:89]
	v_mov_b64_e32 v[46:47], v[86:87]
	v_mov_b64_e32 v[42:43], v[90:91]
	s_waitcnt vmcnt(7)
	v_lshlrev_b32_e32 v34, 16, v32
	v_mul_f32_e32 v21, 0xbfb8aa3b, v34
	v_exp_f32_e32 v21, v21
	v_and_b32_e32 v35, 0xffff0000, v32
	v_add_f32_e32 v21, 1.0, v21
	v_rcp_f32_e32 v36, v21
	v_pk_mul_f32 v[4:5], v[4:5], v[20:21] op_sel_hi:[1,0]
	v_mul_f32_e32 v21, 0xbfb8aa3b, v35
	v_exp_f32_e32 v21, v21
	s_waitcnt vmcnt(6)
	v_pk_mul_f32 v[4:5], v[26:27], v[4:5]
	v_add_f32_e32 v21, 1.0, v21
	v_rcp_f32_e32 v37, v21
	s_nop 0
	v_pk_mul_f32 v[26:27], v[36:37], v[34:35]
	s_nop 0
	v_pk_mul_f32 v[4:5], v[4:5], v[26:27]
	v_lshlrev_b32_e32 v26, 16, v33
	v_mul_f32_e32 v21, 0xbfb8aa3b, v26
	v_exp_f32_e32 v21, v21
	v_and_b32_e32 v27, 0xffff0000, v33
	v_mov_b64_e32 v[36:37], v[92:93]
	v_mov_b64_e32 v[38:39], v[94:95]
	v_add_f32_e32 v21, 1.0, v21
	v_rcp_f32_e32 v32, v21
	v_pk_mul_f32 v[6:7], v[6:7], v[20:21] op_sel_hi:[1,0]
	v_mul_f32_e32 v21, 0xbfb8aa3b, v27
	v_exp_f32_e32 v21, v21
	v_pk_mul_f32 v[6:7], v[28:29], v[6:7]
	v_add_f32_e32 v21, 1.0, v21
	v_rcp_f32_e32 v33, v21
	v_pk_mul_f32 v[8:9], v[8:9], v[20:21] op_sel_hi:[1,0]
	v_pk_mul_f32 v[26:27], v[32:33], v[26:27]
	s_nop 0
	v_pk_mul_f32 v[6:7], v[6:7], v[26:27]
	v_cvt_pk_bf16_f32 v26, v4, v5
	v_cvt_pk_bf16_f32 v27, v6, v7
	v_lshl_add_u64 v[6:7], v[30:31], 0, v[146:147]
	v_lshl_add_u64 v[4:5], v[6:7], 0, s[18:19]
	v_add_co_u32_e32 v6, vcc, s9, v6
	v_readlane_b32 s9, v254, 63
	s_nop 0
	v_addc_co_u32_e32 v7, vcc, 0, v7, vcc
	global_store_dwordx2 v[6:7], v[26:27], off offset:2048
	s_add_i32 s21, s21, s9
	s_andn2_b64 vcc, exec, s[10:11]
	s_mov_b32 s9, s8
	s_waitcnt vmcnt(5)
	v_lshlrev_b32_e32 v30, 16, v162
	v_and_b32_e32 v31, 0xffff0000, v162
	v_mul_f32_e32 v6, 0xbfb8aa3b, v30
	v_exp_f32_e32 v6, v6
	s_waitcnt vmcnt(4)
; __device__ __forceinline__ unsigned pk2(float lo, float hi) { return pg8::pkc(lo, hi); }
; __device__ __forceinline__ void ph_g3(Frame& F, int e, int nrc) {
;     ...
;         for (int g4 = 0; g4 < 4; ++g4) { const int dv0 = 32 * db + 8 * g4 + 4 * hi;
;             const v2u gw = *(const v2u*)(P + row * DINP + C_GB + 128 * h + dv0); const f32x4 gn = *(const f32x4*)(gg + 128 * h + dv0);
;             const float g0 = bflo(gw.x), g1 = bfhi(gw.x), g2 = bflo(gw.y), g3 = bfhi(gw.y);
;             const float y0 = o[4 * g4 + 0] * rn * gn.x * (g0 * __builtin_amdgcn_rcpf(1.0f + __expf(-g0))), y1 = o[4 * g4 + 1] * rn * gn.y * (g1 * __builtin_amdgcn_rcpf(1.0f + __expf(-g1)));
;             const float y2 = o[4 * g4 + 2] * rn * gn.z * (g2 * __builtin_amdgcn_rcpf(1.0f + __expf(-g2))), y3 = o[4 * g4 + 3] * rn * gn.w * (g3 * __builtin_amdgcn_rcpf(1.0f + __expf(-g3)));
;             v2u w; w.x = pk2(y0, y1); w.y = pk2(y2, y3);
;             *(v2u*)(MIX + row * D + 1024 + 128 * h + dv0) = w; }
	v_pk_mul_f32 v[8:9], v[8:9], v[164:165]
	v_add_f32_e32 v6, 1.0, v6
	v_rcp_f32_e32 v32, v6
	v_mul_f32_e32 v6, 0xbfb8aa3b, v31
	v_exp_f32_e32 v6, v6
	s_nop 0
	v_add_f32_e32 v6, 1.0, v6
	v_rcp_f32_e32 v33, v6
	v_lshlrev_b32_e32 v6, 16, v163
	v_mul_f32_e32 v21, 0xbfb8aa3b, v6
	v_exp_f32_e32 v21, v21
	v_pk_mul_f32 v[26:27], v[32:33], v[30:31]
	v_and_b32_e32 v7, 0xffff0000, v163
	v_pk_mul_f32 v[8:9], v[8:9], v[26:27]
	v_add_f32_e32 v21, 1.0, v21
	v_rcp_f32_e32 v26, v21
	v_pk_mul_f32 v[10:11], v[10:11], v[20:21] op_sel_hi:[1,0]
	v_mul_f32_e32 v21, 0xbfb8aa3b, v7
	v_exp_f32_e32 v21, v21
	v_pk_mul_f32 v[10:11], v[10:11], v[166:167]
	v_cvt_pk_bf16_f32 v8, v8, v9
	v_add_f32_e32 v21, 1.0, v21
	v_rcp_f32_e32 v27, v21
	v_pk_mul_f32 v[12:13], v[12:13], v[20:21] op_sel_hi:[1,0]
	v_pk_mul_f32 v[14:15], v[14:15], v[20:21] op_sel_hi:[1,0]
	v_pk_mul_f32 v[16:17], v[16:17], v[20:21] op_sel_hi:[1,0]
	v_pk_mul_f32 v[6:7], v[26:27], v[6:7]
	s_nop 0
	v_pk_mul_f32 v[6:7], v[10:11], v[6:7]
	s_nop 0
	v_cvt_pk_bf16_f32 v9, v6, v7
	global_store_dwordx2 v[4:5], v[8:9], off offset:16
	s_waitcnt vmcnt(3)
	v_lshlrev_b32_e32 v26, 16, v168
	v_and_b32_e32 v27, 0xffff0000, v168
	v_mul_f32_e32 v10, 0xbfb8aa3b, v26
	v_exp_f32_e32 v10, v10
	s_waitcnt vmcnt(2)
	v_pk_mul_f32 v[6:7], v[12:13], v[170:171]
	v_pk_mul_f32 v[8:9], v[14:15], v[172:173]
	v_add_f32_e32 v10, 1.0, v10
	v_rcp_f32_e32 v28, v10
	v_mul_f32_e32 v10, 0xbfb8aa3b, v27
	v_exp_f32_e32 v10, v10
	s_nop 0
	v_add_f32_e32 v10, 1.0, v10
	v_rcp_f32_e32 v29, v10
	v_lshlrev_b32_e32 v10, 16, v169
	v_and_b32_e32 v11, 0xffff0000, v169
	v_pk_mul_f32 v[12:13], v[28:29], v[26:27]
	s_nop 0
	v_pk_mul_f32 v[6:7], v[6:7], v[12:13]
	v_mul_f32_e32 v12, 0xbfb8aa3b, v10
	v_mul_f32_e32 v13, 0xbfb8aa3b, v11
	v_exp_f32_e32 v12, v12
	v_exp_f32_e32 v13, v13
	v_cvt_pk_bf16_f32 v6, v6, v7
	v_add_f32_e32 v12, 1.0, v12
	v_add_f32_e32 v13, 1.0, v13
	v_rcp_f32_e32 v12, v12
	v_rcp_f32_e32 v13, v13
	s_nop 0
	v_pk_mul_f32 v[10:11], v[12:13], v[10:11]
	s_nop 0
	v_pk_mul_f32 v[8:9], v[8:9], v[10:11]
	s_nop 0
	v_cvt_pk_bf16_f32 v7, v8, v9
	global_store_dwordx2 v[4:5], v[6:7], off offset:32
	s_waitcnt vmcnt(1)
	v_lshlrev_b32_e32 v12, 16, v174
	v_and_b32_e32 v13, 0xffff0000, v174
	v_mul_f32_e32 v6, 0xbfb8aa3b, v12
	v_exp_f32_e32 v6, v6
	s_waitcnt vmcnt(0)
	v_pk_mul_f32 v[8:9], v[16:17], v[176:177]
	v_add_f32_e32 v6, 1.0, v6
	v_rcp_f32_e32 v14, v6
	v_mul_f32_e32 v6, 0xbfb8aa3b, v13
	v_exp_f32_e32 v6, v6
	s_nop 0
	v_add_f32_e32 v6, 1.0, v6
	v_rcp_f32_e32 v15, v6
	v_lshlrev_b32_e32 v6, 16, v175
	v_and_b32_e32 v7, 0xffff0000, v175
	v_pk_mul_f32 v[12:13], v[14:15], v[12:13]
	s_nop 0
	v_pk_mul_f32 v[8:9], v[8:9], v[12:13]
	v_mul_f32_e32 v12, 0xbfb8aa3b, v6
	v_mul_f32_e32 v13, 0xbfb8aa3b, v7
	v_exp_f32_e32 v12, v12
	v_exp_f32_e32 v13, v13
	v_pk_mul_f32 v[14:15], v[18:19], v[20:21] op_sel_hi:[1,0]
	v_cvt_pk_bf16_f32 v8, v8, v9
	v_add_f32_e32 v12, 1.0, v12
	v_add_f32_e32 v13, 1.0, v13
	v_rcp_f32_e32 v12, v12
	v_rcp_f32_e32 v13, v13
	v_pk_mul_f32 v[10:11], v[14:15], v[178:179]
	v_mov_b64_e32 v[16:17], v[80:81]
	v_mov_b64_e32 v[20:21], v[76:77]
	v_pk_mul_f32 v[6:7], v[12:13], v[6:7]
	v_mov_b64_e32 v[12:13], v[100:101]
	v_pk_mul_f32 v[6:7], v[10:11], v[6:7]
	v_mov_b64_e32 v[18:19], v[82:83]
	v_cvt_pk_bf16_f32 v9, v6, v7
	global_store_dwordx2 v[4:5], v[8:9], off offset:48
	v_mov_b64_e32 v[4:5], v[96:97]
	v_mov_b64_e32 v[8:9], v[104:105]
	v_mov_b64_e32 v[6:7], v[98:99]
	v_mov_b64_e32 v[22:23], v[78:79]
	v_mov_b64_e32 v[14:15], v[102:103]
	v_mov_b64_e32 v[10:11], v[106:107]
	s_cbranch_vccz .LBB0_1005
